# NA attention stage loop: Q row 1, rpb row 1 and all V fragments read early (ds_read_b64 straight into MFMA operand layout, 12 v_mov per block dropped), counted lgkmcnt waits
# speedup vs baseline: 1.0068x; 1.0068x over previous
.LBB0_202:
	v_add_u32_e32 v0, v93, v88
	v_add_u32_e32 v72, v93, v87
	ds_read_b128 v[50:53], v0 offset:32768
	ds_read_b128 v[54:57], v72 offset:32768
	ds_read_b128 v[156:159], v0 offset:40960
	ds_read_b128 v[160:163], v72 offset:40960
	v_add_u32_e32 v67, s98, v117
	v_add_u32_e32 v62, s99, v117
	s_waitcnt lgkmcnt(2)
	v_mfma_f32_16x16x32_bf16 v[58:61], v[46:49], v[50:53], 0
	v_add_u32_e32 v63, s30, v117
	v_add_u32_e32 v68, s4, v117
	s_add_i32 s10, s81, s8
	v_add_u32_e32 v66, s97, v117
	ds_read2_b32 v[64:65], v68 offset1:1
	ds_read2_b32 v[70:71], v68 offset0:2 offset1:3
	ds_read_b32 v68, v63
	ds_read_b32 v69, v62
	v_mfma_f32_16x16x32_bf16 v[60:63], v[42:45], v[54:57], v[58:61]
	s_nop 2
	ds_read_b32 v58, v67
	ds_read_b32 v59, v66
	v_add_u32_e32 v172, v128, v116
	v_add_u32_e32 v173, 0x10364, v172
	v_add_u32_e32 v174, 0x1036c, v172
	v_add_u32_e32 v175, 0x103a4, v172
	v_add_u32_e32 v172, 0x103ac, v172
	ds_read2_b32 v[164:165], v173 offset1:1
	ds_read2_b32 v[166:167], v174 offset1:1
	ds_read2_b32 v[168:169], v175 offset1:1
	ds_read2_b32 v[170:171], v172 offset1:1
	s_cmp_ge_u32 s10, s80
	s_cselect_b64 s[0:1], -1, 0
	v_mfma_f32_16x16x32_bf16 v[50:53], v[6:9], v[50:53], 0
	s_cmp_lt_u32 s10, s89
	s_cselect_b64 s[8:9], -1, 0
	s_and_b64 s[0:1], s[0:1], s[8:9]
	s_waitcnt lgkmcnt(4)
	v_mfma_f32_16x16x32_bf16 v[50:53], v[2:5], v[54:57], v[50:53]
	v_add_u32_e32 v172, s6, v107
	v_add3_u32 v154, v172, v82, v83
	v_add_u32_e32 v172, s6, v106
	v_add3_u32 v155, v172, v82, v83
	ds_read_b64 v[176:177], v154 offset:8192
	ds_read_b64 v[178:179], v155 offset:8192
	ds_read_b64 v[180:181], v154 offset:10240
	ds_read_b64 v[182:183], v155 offset:10240
	ds_read_b64 v[236:237], v154 offset:12288
	ds_read_b64 v[238:239], v155 offset:12288
	ds_read_b64 v[244:245], v154 offset:14336
	ds_read_b64 v[246:247], v155 offset:14336
	v_add_f32_e32 v54, v59, v60
	s_and_b64 vcc, s[0:1], s[40:41]
	v_cndmask_b32_e32 v60, v196, v54, vcc
	v_add_f32_e32 v54, v58, v61
	s_and_b64 vcc, s[0:1], s[42:43]
	v_cndmask_b32_e32 v61, v196, v54, vcc
	v_add_f32_e32 v54, v69, v62
	s_and_b64 vcc, s[0:1], s[44:45]
	v_cndmask_b32_e32 v66, v196, v54, vcc
	v_add_f32_e32 v54, v68, v63
	s_and_b64 vcc, s[0:1], s[46:47]
	v_cndmask_b32_e32 v67, v196, v54, vcc
	v_add_f32_e32 v50, v64, v50
	s_and_b64 vcc, s[0:1], s[48:49]
	v_cndmask_b32_e32 v68, v196, v50, vcc
	v_add_f32_e32 v50, v65, v51
	s_and_b64 vcc, s[0:1], s[50:51]
	v_cndmask_b32_e32 v69, v196, v50, vcc
	v_add_f32_e32 v50, v70, v52
	s_and_b64 vcc, s[0:1], s[52:53]
	v_cndmask_b32_e32 v76, v196, v50, vcc
	v_add_f32_e32 v50, v71, v53
	s_and_b64 vcc, s[0:1], s[54:55]
	v_cndmask_b32_e32 v77, v196, v50, vcc
	v_mfma_f32_16x16x32_bf16 v[46:49], v[46:49], v[156:159], 0
	s_cmp_ge_u32 s10, s56
	v_mfma_f32_16x16x32_bf16 v[6:9], v[6:9], v[156:159], 0
	s_cselect_b64 s[0:1], -1, 0
	s_cmp_lt_u32 s10, s57
	s_cselect_b64 s[8:9], -1, 0
	s_and_b64 s[0:1], s[0:1], s[8:9]
	v_mfma_f32_16x16x32_bf16 v[42:45], v[42:45], v[160:163], v[46:49]
	s_and_b64 vcc, s[0:1], s[40:41]
	v_mfma_f32_16x16x32_bf16 v[2:5], v[2:5], v[160:163], v[6:9]
	v_mov_b64_e32 v[56:57], v[20:21]
	v_mov_b64_e32 v[52:53], v[40:41]
	s_waitcnt lgkmcnt(8)
	s_nop 3
	v_add_f32_e32 v6, v164, v42
	v_cndmask_b32_e32 v130, v196, v6, vcc
	v_add_f32_e32 v6, v165, v43
	s_and_b64 vcc, s[0:1], s[42:43]
	v_cndmask_b32_e32 v131, v196, v6, vcc
	v_add_f32_e32 v6, v166, v44
	s_and_b64 vcc, s[0:1], s[44:45]
	v_cndmask_b32_e32 v132, v196, v6, vcc
	v_add_f32_e32 v6, v167, v45
	s_and_b64 vcc, s[0:1], s[46:47]
	v_cndmask_b32_e32 v133, v196, v6, vcc
	v_add_f32_e32 v2, v168, v2
	s_and_b64 vcc, s[0:1], s[48:49]
	v_cndmask_b32_e32 v136, v196, v2, vcc
	v_add_f32_e32 v2, v169, v3
	s_and_b64 vcc, s[0:1], s[50:51]
	v_cndmask_b32_e32 v137, v196, v2, vcc
	v_add_f32_e32 v0, v170, v4
	s_and_b64 vcc, s[0:1], s[52:53]
	v_cndmask_b32_e32 v138, v196, v0, vcc
	v_add_f32_e32 v0, v171, v5
	s_and_b64 vcc, s[0:1], s[54:55]
	v_max_f32_e32 v3, v76, v77
	v_cndmask_b32_e32 v139, v196, v0, vcc
	v_max_f32_e32 v0, v60, v61
	v_max_f32_e32 v2, v66, v67
	v_max3_f32 v3, v68, v69, v3
	v_max3_f32 v143, v0, v2, v3
	v_add_f32_e32 v0, 0x41000000, v75
	v_max_f32_e32 v3, v138, v139
	v_cmp_gt_f32_e32 vcc, v143, v0
	v_max_f32_e32 v0, v130, v131
	v_max_f32_e32 v2, v132, v133
	v_max3_f32 v3, v136, v137, v3
	v_max3_f32 v142, v0, v2, v3
	v_add_f32_e32 v0, 0x41000000, v74
	v_cmp_gt_f32_e64 s[0:1], v142, v0
	v_mov_b64_e32 v[64:65], v[12:13]
	v_mov_b64_e32 v[72:73], v[28:29]
	v_mov_b64_e32 v[44:45], v[32:33]
	v_mov_b64_e32 v[6:7], v[14:15]
	v_mov_b64_e32 v[2:3], v[22:23]
	v_mov_b64_e32 v[48:49], v[36:37]
	s_or_b64 vcc, vcc, s[0:1]
	v_mov_b32_e32 v140, v74
	v_mov_b32_e32 v141, v75
	v_mov_b64_e32 v[62:63], v[10:11]
	v_mov_b64_e32 v[54:55], v[18:19]
	v_mov_b64_e32 v[70:71], v[26:27]
	v_mov_b64_e32 v[42:43], v[30:31]
	v_mov_b64_e32 v[8:9], v[16:17]
	v_mov_b64_e32 v[4:5], v[24:25]
	v_mov_b64_e32 v[46:47], v[34:35]
	v_mov_b64_e32 v[50:51], v[38:39]
	v_mov_b64_e32 v[58:59], v[78:79]
	v_mov_b32_e32 v129, v74
	v_mov_b32_e32 v0, v75
	s_cbranch_vccz .LBB0_204
	ds_bpermute_b32 v0, v186, v143
	v_max_f32_e32 v2, v143, v143
	ds_bpermute_b32 v3, v186, v142
	v_max_f32_e32 v4, v142, v142
	s_waitcnt lgkmcnt(0)
	v_max_f32_e32 v0, v0, v0
	v_max_f32_e32 v0, v2, v0
	ds_bpermute_b32 v2, v187, v0
	s_waitcnt lgkmcnt(0)
	v_max3_f32 v141, v75, v0, v2
	v_max_f32_e32 v2, v3, v3
	v_max_f32_e32 v6, v4, v2
	ds_bpermute_b32 v7, v187, v6
	v_sub_f32_e32 v0, v75, v141
	v_exp_f32_e32 v0, v0
	s_waitcnt lgkmcnt(0)
	v_max3_f32 v140, v74, v6, v7
	v_sub_f32_e32 v6, v74, v140
	v_exp_f32_e32 v62, v6
	v_mov_b32_e32 v63, v0
	v_pk_mul_f32 v[52:53], v[40:41], v[0:1] op_sel_hi:[1,0]
	v_pk_mul_f32 v[50:51], v[38:39], v[0:1] op_sel_hi:[1,0]
	v_pk_mul_f32 v[48:49], v[36:37], v[0:1] op_sel_hi:[1,0]
	v_pk_mul_f32 v[46:47], v[34:35], v[0:1] op_sel_hi:[1,0]
	v_pk_mul_f32 v[4:5], v[24:25], v[0:1] op_sel_hi:[1,0]
	v_pk_mul_f32 v[2:3], v[22:23], v[0:1] op_sel_hi:[1,0]
	v_pk_mul_f32 v[8:9], v[16:17], v[0:1] op_sel_hi:[1,0]
	v_pk_mul_f32 v[6:7], v[14:15], v[0:1] op_sel_hi:[1,0]
	v_pk_mul_f32 v[58:59], v[78:79], v[62:63]
	v_pk_mul_f32 v[44:45], v[32:33], v[62:63] op_sel_hi:[1,0]
	v_pk_mul_f32 v[42:43], v[30:31], v[62:63] op_sel_hi:[1,0]
	v_pk_mul_f32 v[72:73], v[28:29], v[62:63] op_sel_hi:[1,0]
	v_pk_mul_f32 v[70:71], v[26:27], v[62:63] op_sel_hi:[1,0]
	v_pk_mul_f32 v[56:57], v[20:21], v[62:63] op_sel_hi:[1,0]
	v_pk_mul_f32 v[54:55], v[18:19], v[62:63] op_sel_hi:[1,0]
	v_pk_mul_f32 v[64:65], v[12:13], v[62:63] op_sel_hi:[1,0]
	v_pk_mul_f32 v[62:63], v[10:11], v[62:63] op_sel_hi:[1,0]
	v_mov_b32_e32 v129, v140
	v_mov_b32_e32 v0, v141
.LBB0_204:
	v_sub_f32_e32 v60, v60, v141
	v_exp_f32_e32 v147, v60
	v_sub_f32_e32 v60, v61, v141
	v_exp_f32_e32 v61, v60
	v_sub_f32_e32 v60, v66, v141
	v_exp_f32_e32 v149, v60
	v_sub_f32_e32 v60, v67, v141
	v_exp_f32_e32 v67, v60
	v_sub_f32_e32 v60, v68, v141
	v_exp_f32_e32 v151, v60
	v_sub_f32_e32 v60, v69, v141
	v_exp_f32_e32 v69, v60
	v_sub_f32_e32 v60, v76, v141
	v_exp_f32_e32 v153, v60
	v_sub_f32_e32 v60, v77, v141
	v_exp_f32_e32 v141, v60
	v_sub_f32_e32 v60, v130, v140
	v_exp_f32_e32 v146, v60
	v_sub_f32_e32 v60, v131, v140
	v_exp_f32_e32 v60, v60
	v_sub_f32_e32 v66, v132, v140
	v_exp_f32_e32 v148, v66
	v_sub_f32_e32 v66, v133, v140
	v_sub_f32_e32 v76, v138, v140
	v_exp_f32_e32 v66, v66
	v_sub_f32_e32 v68, v136, v140
	v_exp_f32_e32 v152, v76
	v_sub_f32_e32 v76, v139, v140
	v_exp_f32_e32 v150, v68
	v_sub_f32_e32 v68, v137, v140
	v_exp_f32_e32 v140, v76
	v_pk_add_f32 v[76:77], v[146:147], 0 op_sel_hi:[1,0]
	v_exp_f32_e32 v68, v68
	v_pk_add_f32 v[76:77], v[60:61], v[76:77]
	v_pk_add_f32 v[76:77], v[148:149], v[76:77]
	v_pk_add_f32 v[76:77], v[66:67], v[76:77]
	v_pk_add_f32 v[76:77], v[150:151], v[76:77]
	v_cvt_pk_bf16_f32 v143, v149, v67
	v_cvt_pk_bf16_f32 v144, v151, v69
	v_pk_add_f32 v[76:77], v[68:69], v[76:77]
	v_cvt_pk_bf16_f32 v131, v148, v66
	v_cvt_pk_bf16_f32 v132, v150, v68
	v_cvt_pk_bf16_f32 v142, v147, v61
	v_cvt_pk_bf16_f32 v145, v153, v141
	v_cvt_pk_bf16_f32 v130, v146, v60
	v_cvt_pk_bf16_f32 v133, v152, v140
	s_waitcnt lgkmcnt(0)
	v_mfma_f32_16x16x32_bf16 v[66:69], v[180:183], v[142:145], v[46:49]
	v_add_f32_e64 v76, v152, v76
	v_add_f32_e64 v77, v153, v77
	v_pk_add_f32 v[76:77], v[140:141], v[76:77]
	v_mfma_f32_16x16x32_bf16 v[46:49], v[180:183], v[130:133], v[70:73]
	v_pk_add_f32 v[76:77], v[58:59], v[76:77]
	v_mfma_f32_16x16x32_bf16 v[58:61], v[176:179], v[142:145], v[50:53]
	v_mfma_f32_16x16x32_bf16 v[42:45], v[176:179], v[130:133], v[42:45]
	v_mfma_f32_16x16x32_bf16 v[50:53], v[236:239], v[142:145], v[2:5]
	v_mfma_f32_16x16x32_bf16 v[2:5], v[236:239], v[130:133], v[54:57]
	v_mfma_f32_16x16x32_bf16 v[54:57], v[244:247], v[142:145], v[6:9]
	v_mfma_f32_16x16x32_bf16 v[6:9], v[244:247], v[130:133], v[62:65]
	s_mov_b64 s[0:1], 0

.LBB0_212:
	v_add_u32_e32 v60, v93, v88
	ds_read_b128 v[2:5], v60 offset:32768
	v_add_u32_e32 v0, v93, v87
	ds_read_b128 v[62:65], v0 offset:32768
	ds_read_b128 v[156:159], v60 offset:40960
	ds_read_b128 v[160:163], v0 offset:40960
	s_waitcnt lgkmcnt(2)
	v_mfma_f32_16x16x32_bf16 v[42:45], v[6:9], v[2:5], 0
	v_mfma_f32_16x16x32_bf16 v[2:5], v[50:53], v[2:5], 0
	v_mfma_f32_16x16x32_bf16 v[42:45], v[46:49], v[62:65], v[42:45]
	v_mfma_f32_16x16x32_bf16 v[2:5], v[54:57], v[62:65], v[2:5]
	v_add_u32_e32 v172, s6, v86
	v_add3_u32 v173, v172, v82, v83
	v_add_u32_e32 v172, s6, v85
	v_add3_u32 v174, v172, v82, v83
	ds_read_b64 v[176:177], v173 offset:8192
	ds_read_b64 v[178:179], v174 offset:8192
	ds_read_b64 v[180:181], v173 offset:10240
	ds_read_b64 v[182:183], v174 offset:10240
	ds_read_b64 v[236:237], v173 offset:12288
	ds_read_b64 v[238:239], v174 offset:12288
	ds_read_b64 v[244:245], v173 offset:14336
	ds_read_b64 v[246:247], v174 offset:14336
	s_waitcnt lgkmcnt(8)
	v_mfma_f32_16x16x32_bf16 v[6:9], v[6:9], v[156:159], 0
	v_mfma_f32_16x16x32_bf16 v[46:49], v[46:49], v[160:163], v[6:9]
	v_mfma_f32_16x16x32_bf16 v[6:9], v[50:53], v[156:159], 0
	s_nop 0
	v_max_f32_e32 v50, v43, v43
	v_max_f32_e32 v51, v42, v42
	v_max_f32_e32 v50, v51, v50
	v_max_f32_e32 v51, v45, v45
	v_max_f32_e32 v52, v44, v44
	v_max_f32_e32 v51, v52, v51
	v_max_f32_e32 v52, v5, v5
	v_max_f32_e32 v53, v4, v4
	v_mfma_f32_16x16x32_bf16 v[6:9], v[54:57], v[160:163], v[6:9]
	v_max_f32_e32 v52, v53, v52
	v_max3_f32 v52, v2, v3, v52
	v_max3_f32 v51, v50, v51, v52
	v_max_f32_e32 v50, v47, v47
	v_max_f32_e32 v54, v46, v46
	v_max_f32_e32 v50, v54, v50
	v_max_f32_e32 v54, v49, v49
	v_max_f32_e32 v55, v48, v48
	v_max_f32_e32 v54, v55, v54
	v_max_f32_e32 v55, v9, v9
	v_max_f32_e32 v56, v8, v8
	v_max_f32_e32 v55, v56, v55
	v_max3_f32 v55, v6, v7, v55
	v_pk_add_f32 v[52:53], v[74:75], s[12:13] op_sel_hi:[1,0]
	v_max3_f32 v50, v50, v54, v55
	v_cmp_gt_f32_e32 vcc, v51, v53
	v_cmp_gt_f32_e64 s[0:1], v50, v52
	s_or_b64 vcc, vcc, s[0:1]
	s_cbranch_vccz .LBB0_214
	ds_bpermute_b32 v52, v186, v51
	v_max_f32_e32 v51, v51, v51
	s_waitcnt lgkmcnt(0)
	v_max_f32_e32 v52, v52, v52
	v_max_f32_e32 v51, v51, v52
	ds_bpermute_b32 v52, v187, v51
	s_waitcnt lgkmcnt(0)
	v_max3_f32 v51, v75, v51, v52
	v_sub_f32_e32 v52, v75, v51
	v_exp_f32_e32 v52, v52
	v_mov_b32_e32 v75, v51
	v_pk_mul_f32 v[40:41], v[40:41], v[52:53] op_sel_hi:[1,0]
	v_pk_mul_f32 v[38:39], v[38:39], v[52:53] op_sel_hi:[1,0]
	v_pk_mul_f32 v[36:37], v[36:37], v[52:53] op_sel_hi:[1,0]
	v_pk_mul_f32 v[34:35], v[34:35], v[52:53] op_sel_hi:[1,0]
	v_pk_mul_f32 v[24:25], v[24:25], v[52:53] op_sel_hi:[1,0]
	v_pk_mul_f32 v[22:23], v[22:23], v[52:53] op_sel_hi:[1,0]
	v_pk_mul_f32 v[16:17], v[16:17], v[52:53] op_sel_hi:[1,0]
	v_pk_mul_f32 v[14:15], v[14:15], v[52:53] op_sel_hi:[1,0]
	ds_bpermute_b32 v53, v186, v50
	v_max_f32_e32 v50, v50, v50
	v_mov_b32_e32 v55, v52
	s_waitcnt lgkmcnt(0)
	v_max_f32_e32 v53, v53, v53
	v_max_f32_e32 v50, v50, v53
	ds_bpermute_b32 v53, v187, v50
	s_waitcnt lgkmcnt(0)
	v_max3_f32 v50, v74, v50, v53
	v_sub_f32_e32 v53, v74, v50
	v_exp_f32_e32 v54, v53
	v_pk_add_f32 v[52:53], v[50:51], s[12:13] op_sel_hi:[1,0]
	v_mov_b32_e32 v74, v50
	v_pk_mul_f32 v[78:79], v[78:79], v[54:55]
	v_pk_mul_f32 v[32:33], v[32:33], v[54:55] op_sel_hi:[1,0]
	v_pk_mul_f32 v[30:31], v[30:31], v[54:55] op_sel_hi:[1,0]
	v_pk_mul_f32 v[28:29], v[28:29], v[54:55] op_sel_hi:[1,0]
	v_pk_mul_f32 v[26:27], v[26:27], v[54:55] op_sel_hi:[1,0]
	v_pk_mul_f32 v[20:21], v[20:21], v[54:55] op_sel_hi:[1,0]
	v_pk_mul_f32 v[18:19], v[18:19], v[54:55] op_sel_hi:[1,0]
	v_pk_mul_f32 v[12:13], v[12:13], v[54:55] op_sel_hi:[1,0]
	v_pk_mul_f32 v[10:11], v[10:11], v[54:55] op_sel_hi:[1,0]
.LBB0_214:
	v_sub_f32_e32 v2, v2, v75
	v_exp_f32_e32 v67, v2
	v_sub_f32_e32 v2, v3, v75
	v_exp_f32_e32 v3, v2
	v_sub_f32_e32 v2, v4, v75
	v_exp_f32_e32 v69, v2
	v_sub_f32_e32 v2, v5, v75
	v_sub_f32_e32 v42, v42, v75
	v_exp_f32_e32 v5, v2
	v_sub_f32_e32 v2, v46, v74
	v_exp_f32_e32 v55, v42
	v_sub_f32_e32 v42, v43, v75
	v_exp_f32_e32 v54, v2
	v_sub_f32_e32 v2, v47, v74
	v_exp_f32_e32 v57, v42
	v_sub_f32_e32 v42, v44, v75
	v_exp_f32_e32 v56, v2
	v_sub_f32_e32 v2, v48, v74
	v_exp_f32_e32 v63, v42
	v_sub_f32_e32 v42, v45, v75
	v_exp_f32_e32 v62, v2
	v_sub_f32_e32 v2, v49, v74
	v_exp_f32_e32 v65, v42
	v_exp_f32_e32 v64, v2
	v_sub_f32_e32 v2, v6, v74
	v_pk_add_f32 v[46:47], v[54:55], 0 op_sel_hi:[1,0]
	v_exp_f32_e32 v66, v2
	v_sub_f32_e32 v2, v7, v74
	v_pk_add_f32 v[46:47], v[56:57], v[46:47]
	v_exp_f32_e32 v2, v2
	v_sub_f32_e32 v4, v8, v74
	v_exp_f32_e32 v68, v4
	v_sub_f32_e32 v4, v9, v74
	v_pk_add_f32 v[6:7], v[62:63], v[46:47]
	v_exp_f32_e32 v4, v4
	v_pk_add_f32 v[6:7], v[64:65], v[6:7]
	v_pk_add_f32 v[6:7], v[66:67], v[6:7]
	v_pk_add_f32 v[6:7], v[2:3], v[6:7]
	v_pk_add_f32 v[6:7], v[68:69], v[6:7]
	v_cvt_pk_bf16_f32 v44, v67, v3
	v_cvt_pk_bf16_f32 v45, v69, v5
	v_pk_add_f32 v[6:7], v[4:5], v[6:7]
	v_cvt_pk_bf16_f32 v8, v66, v2
	v_cvt_pk_bf16_f32 v9, v68, v4
	v_cvt_pk_bf16_f32 v42, v55, v57
	v_pk_add_f32 v[50:51], v[78:79], v[6:7]
	v_cvt_pk_bf16_f32 v6, v54, v56
	s_waitcnt lgkmcnt(0)
	v_cvt_pk_bf16_f32 v43, v63, v65
	v_cvt_pk_bf16_f32 v7, v62, v64
	s_nop 0
	v_mfma_f32_16x16x32_bf16 v[38:41], v[176:179], v[42:45], v[38:41]
	v_mfma_f32_16x16x32_bf16 v[30:33], v[176:179], v[6:9], v[30:33]
	v_mfma_f32_16x16x32_bf16 v[34:37], v[180:183], v[42:45], v[34:37]
	v_mfma_f32_16x16x32_bf16 v[26:29], v[180:183], v[6:9], v[26:29]
	v_mfma_f32_16x16x32_bf16 v[22:25], v[236:239], v[42:45], v[22:25]
	v_mfma_f32_16x16x32_bf16 v[2:5], v[236:239], v[6:9], v[18:21]
	v_mfma_f32_16x16x32_bf16 v[14:17], v[244:247], v[42:45], v[14:17]
	v_mfma_f32_16x16x32_bf16 v[6:9], v[244:247], v[6:9], v[10:13]
	ds_read_b128 v[42:45], v58 offset:4096
	ds_read_b128 v[46:49], v59 offset:4096
	ds_read_b128 v[54:57], v58 offset:6144
	ds_read_b128 v[62:65], v59 offset:6144
	ds_read_b128 v[10:13], v60 offset:32768
	ds_read_b128 v[66:69], v0 offset:32768
	ds_read_b128 v[156:159], v60 offset:40960
	ds_read_b128 v[160:163], v0 offset:40960
	s_waitcnt lgkmcnt(2)
	v_mfma_f32_16x16x32_bf16 v[18:21], v[42:45], v[10:13], 0
	v_mfma_f32_16x16x32_bf16 v[10:13], v[54:57], v[10:13], 0
	v_mfma_f32_16x16x32_bf16 v[18:21], v[46:49], v[66:69], v[18:21]
	v_mfma_f32_16x16x32_bf16 v[10:13], v[62:65], v[66:69], v[10:13]
	v_add_u32_e32 v172, s6, v84
	v_add3_u32 v173, v172, v82, v83
	v_add_u32_e32 v172, s6, v81
	v_add3_u32 v174, v172, v82, v83
	ds_read_b64 v[176:177], v173 offset:8192
	ds_read_b64 v[178:179], v174 offset:8192
	ds_read_b64 v[180:181], v173 offset:10240
	ds_read_b64 v[182:183], v174 offset:10240
	ds_read_b64 v[236:237], v173 offset:12288
	ds_read_b64 v[238:239], v174 offset:12288
	ds_read_b64 v[244:245], v173 offset:14336
	ds_read_b64 v[246:247], v174 offset:14336
	v_max_f32_e32 v0, v19, v19
	s_waitcnt lgkmcnt(8)
	v_mfma_f32_16x16x32_bf16 v[42:45], v[42:45], v[156:159], 0
	v_mfma_f32_16x16x32_bf16 v[46:49], v[46:49], v[160:163], v[42:45]
	v_mfma_f32_16x16x32_bf16 v[42:45], v[54:57], v[156:159], 0
	v_max_f32_e32 v54, v18, v18
	v_max_f32_e32 v0, v54, v0
	v_max_f32_e32 v54, v21, v21
	v_max_f32_e32 v55, v20, v20
	v_max_f32_e32 v54, v55, v54
	v_max_f32_e32 v55, v13, v13
	v_max_f32_e32 v56, v12, v12
	v_max_f32_e32 v55, v56, v55
	v_mfma_f32_16x16x32_bf16 v[42:45], v[62:65], v[160:163], v[42:45]
	v_max3_f32 v55, v10, v11, v55
	v_max3_f32 v54, v0, v54, v55
	v_cmp_gt_f32_e32 vcc, v54, v53
	v_max_f32_e32 v0, v47, v47
	v_max_f32_e32 v53, v46, v46
	v_max_f32_e32 v0, v53, v0
	v_max_f32_e32 v53, v49, v49
	v_max_f32_e32 v55, v48, v48
	v_max_f32_e32 v53, v55, v53
	v_max_f32_e32 v55, v45, v45
	v_max_f32_e32 v56, v44, v44
	v_max_f32_e32 v55, v56, v55
	v_max3_f32 v55, v42, v43, v55
	v_max3_f32 v0, v0, v53, v55
	v_cmp_gt_f32_e64 s[0:1], v0, v52
	s_or_b64 vcc, vcc, s[0:1]
	s_cbranch_vccz .LBB0_216
	ds_bpermute_b32 v52, v186, v54
	v_max_f32_e32 v53, v54, v54
	ds_bpermute_b32 v54, v186, v0
	v_max_f32_e32 v0, v0, v0
	s_waitcnt lgkmcnt(0)
	v_max_f32_e32 v52, v52, v52
	v_max_f32_e32 v52, v53, v52
	v_max_f32_e32 v54, v54, v54
	ds_bpermute_b32 v53, v187, v52
	v_max_f32_e32 v0, v0, v54
	ds_bpermute_b32 v54, v187, v0
	s_waitcnt lgkmcnt(0)
	v_max3_f32 v53, v75, v52, v53
	v_sub_f32_e32 v52, v75, v53
	v_max3_f32 v0, v74, v0, v54
	v_exp_f32_e32 v52, v52
	v_sub_f32_e32 v54, v74, v0
	v_exp_f32_e32 v54, v54
	v_mov_b32_e32 v74, v0
	v_mov_b32_e32 v55, v52
	v_pk_mul_f32 v[40:41], v[40:41], v[52:53] op_sel_hi:[1,0]
	v_pk_mul_f32 v[38:39], v[38:39], v[52:53] op_sel_hi:[1,0]
	v_pk_mul_f32 v[36:37], v[36:37], v[52:53] op_sel_hi:[1,0]
	v_pk_mul_f32 v[34:35], v[34:35], v[52:53] op_sel_hi:[1,0]
	v_pk_mul_f32 v[24:25], v[24:25], v[52:53] op_sel_hi:[1,0]
	v_pk_mul_f32 v[22:23], v[22:23], v[52:53] op_sel_hi:[1,0]
	v_pk_mul_f32 v[16:17], v[16:17], v[52:53] op_sel_hi:[1,0]
	v_pk_mul_f32 v[14:15], v[14:15], v[52:53] op_sel_hi:[1,0]
	v_pk_mul_f32 v[50:51], v[50:51], v[54:55]
	v_pk_mul_f32 v[32:33], v[32:33], v[54:55] op_sel_hi:[1,0]
	v_pk_mul_f32 v[30:31], v[30:31], v[54:55] op_sel_hi:[1,0]
	v_pk_mul_f32 v[28:29], v[28:29], v[54:55] op_sel_hi:[1,0]
	v_pk_mul_f32 v[26:27], v[26:27], v[54:55] op_sel_hi:[1,0]
	v_pk_mul_f32 v[4:5], v[4:5], v[54:55] op_sel_hi:[1,0]
	v_pk_mul_f32 v[2:3], v[2:3], v[54:55] op_sel_hi:[1,0]
	v_pk_mul_f32 v[8:9], v[8:9], v[54:55] op_sel_hi:[1,0]
	v_pk_mul_f32 v[6:7], v[6:7], v[54:55] op_sel_hi:[1,0]
	v_mov_b32_e32 v75, v53
.LBB0_216:
	v_sub_f32_e32 v18, v18, v75
	v_exp_f32_e32 v53, v18
	v_sub_f32_e32 v18, v19, v75
	v_exp_f32_e32 v19, v18
	v_sub_f32_e32 v18, v20, v75
	v_exp_f32_e32 v55, v18
	v_sub_f32_e32 v18, v21, v75
	v_exp_f32_e32 v21, v18
	v_sub_f32_e32 v18, v46, v74
	v_exp_f32_e32 v52, v18
	v_sub_f32_e32 v18, v47, v74
	v_sub_f32_e32 v42, v42, v74
	v_exp_f32_e32 v18, v18
	v_sub_f32_e32 v20, v48, v74
	v_exp_f32_e32 v56, v42
	v_sub_f32_e32 v42, v43, v74
	v_exp_f32_e32 v54, v20
	v_sub_f32_e32 v20, v49, v74
	v_exp_f32_e32 v58, v42
	v_sub_f32_e32 v42, v44, v74
	v_sub_f32_e32 v10, v10, v75
	v_exp_f32_e32 v20, v20
	v_exp_f32_e32 v60, v42
	v_sub_f32_e32 v42, v45, v74
	v_exp_f32_e32 v57, v10
	v_sub_f32_e32 v10, v11, v75
	v_exp_f32_e32 v62, v42
	v_pk_add_f32 v[42:43], v[52:53], 0 op_sel_hi:[1,0]
	v_exp_f32_e32 v59, v10
	v_sub_f32_e32 v10, v12, v75
	v_pk_add_f32 v[42:43], v[18:19], v[42:43]
	v_exp_f32_e32 v61, v10
	v_sub_f32_e32 v10, v13, v75
	v_pk_add_f32 v[42:43], v[54:55], v[42:43]
	v_exp_f32_e32 v63, v10
	v_pk_add_f32 v[42:43], v[20:21], v[42:43]
	v_pk_add_f32 v[42:43], v[56:57], v[42:43]
	v_pk_add_f32 v[42:43], v[58:59], v[42:43]
	v_cvt_pk_bf16_f32 v10, v53, v19
	v_pk_add_f32 v[42:43], v[60:61], v[42:43]
	v_cvt_pk_bf16_f32 v11, v55, v21
	v_pk_add_f32 v[42:43], v[62:63], v[42:43]
	v_cvt_pk_bf16_f32 v12, v57, v59
	v_pk_add_f32 v[76:77], v[50:51], v[42:43]
	v_cvt_pk_bf16_f32 v13, v61, v63
	v_cvt_pk_bf16_f32 v18, v52, v18
	v_cvt_pk_bf16_f32 v19, v54, v20
	s_waitcnt lgkmcnt(0)
	v_cvt_pk_bf16_f32 v20, v56, v58
	v_cvt_pk_bf16_f32 v21, v60, v62
	v_mfma_f32_16x16x32_bf16 v[58:61], v[176:179], v[10:13], v[38:41]
	s_nop 0
	v_mfma_f32_16x16x32_bf16 v[42:45], v[176:179], v[18:21], v[30:33]
	v_mfma_f32_16x16x32_bf16 v[66:69], v[180:183], v[10:13], v[34:37]
	v_mfma_f32_16x16x32_bf16 v[46:49], v[180:183], v[18:21], v[26:29]
	v_mfma_f32_16x16x32_bf16 v[50:53], v[236:239], v[10:13], v[22:25]
	v_mfma_f32_16x16x32_bf16 v[2:5], v[236:239], v[18:21], v[2:5]
	v_mfma_f32_16x16x32_bf16 v[54:57], v[244:247], v[10:13], v[14:17]
	v_mfma_f32_16x16x32_bf16 v[6:9], v[244:247], v[18:21], v[6:9]
	v_mov_b32_e32 v0, v75
	v_mov_b32_e32 v129, v74
